# v85: attention item epilogue: 30 weight/gate loads of steps 1..15 hoisted after step 0's loads into idle regs, counted waits
# speedup vs baseline: 1.0053x; 1.0006x over previous
.LBB0_359:
	s_or_b64 exec, exec, s[6:7]
	v_lshl_add_u32 v0, v145, 3, 0
	v_add_u32_e32 v0, 0x1a800, v0
	s_waitcnt lgkmcnt(0)
	s_barrier
	ds_read2st64_b64 v[66:69], v0 offset1:2
	v_readlane_b32 s6, v255, 26
	v_readlane_b32 s7, v255, 27
	s_lshl_b64 s[6:7], s[6:7], 2
	s_add_i32 s8, s8, s57
	v_lshl_add_u64 v[72:73], v[138:139], 0, s[6:7]
	s_waitcnt lgkmcnt(0)
	v_pk_add_f32 v[66:67], v[66:67], v[68:69]
	s_mov_b32 s6, 0x3b800000
	v_pk_mul_f32 v[66:67], v[66:67], s[6:7] op_sel_hi:[1,0]
	s_mov_b32 s6, 0x800000
	v_fma_f32 v0, -v66, v66, v67
	v_max_f32_e32 v0, 0, v0
	v_add_f32_e32 v0, 0x3727c5ac, v0
	v_cmp_gt_f32_e32 vcc, s6, v0
	v_mul_f32_e32 v68, 0x4b800000, v0
	v_lshl_or_b32 v70, v144, 2, s8
	v_cndmask_b32_e32 v0, v0, v68, vcc
	v_rsq_f32_e32 v0, v0
	s_mov_b64 s[6:7], 0x5000
	v_ashrrev_i32_e32 v71, 31, v70
	v_lshlrev_b64 v[80:81], 1, v[70:71]
	v_mul_f32_e32 v68, 0x45800000, v0
	v_cndmask_b32_e32 v0, v0, v68, vcc
	v_lshl_add_u64 v[68:69], v[142:143], 0, s[6:7]
	v_lshlrev_b64 v[74:75], 13, v[140:141]
	v_lshl_add_u64 v[72:73], v[70:71], 2, v[72:73]
	v_lshl_add_u64 v[82:83], v[68:69], 0, v[80:81]
	v_lshl_add_u64 v[78:79], s[0:1], 0, v[74:75]
	global_load_dwordx4 v[74:77], v[72:73], off
	v_pk_add_f32 v[50:51], v[50:51], v[66:67] op_sel_hi:[1,0] neg_lo:[0,1] neg_hi:[0,1]
	global_load_dwordx2 v[82:83], v[82:83], off
	global_load_dwordx4 v[84:87], v[72:73], off offset:32
	v_or_b32_e32 v152, 8, v70
	v_ashrrev_i32_e32 v153, 31, v152
	v_lshl_add_u64 v[152:153], v[152:153], 1, v[68:69]
	global_load_dwordx2 v[178:179], v[152:153], off
	global_load_dwordx4 v[88:91], v[72:73], off offset:64
	v_or_b32_e32 v152, 16, v70
	v_ashrrev_i32_e32 v153, 31, v152
	v_lshl_add_u64 v[152:153], v[152:153], 1, v[68:69]
	global_load_dwordx2 v[180:181], v[152:153], off
	global_load_dwordx4 v[92:95], v[72:73], off offset:96
	v_or_b32_e32 v152, 24, v70
	v_ashrrev_i32_e32 v153, 31, v152
	v_lshl_add_u64 v[152:153], v[152:153], 1, v[68:69]
	global_load_dwordx2 v[182:183], v[152:153], off
	global_load_dwordx4 v[96:99], v[72:73], off offset:128
	v_or_b32_e32 v152, 32, v70
	v_ashrrev_i32_e32 v153, 31, v152
	v_lshl_add_u64 v[152:153], v[152:153], 1, v[68:69]
	global_load_dwordx2 v[184:185], v[152:153], off
	global_load_dwordx4 v[100:103], v[72:73], off offset:160
	v_or_b32_e32 v152, 40, v70
	v_ashrrev_i32_e32 v153, 31, v152
	v_lshl_add_u64 v[152:153], v[152:153], 1, v[68:69]
	global_load_dwordx2 v[186:187], v[152:153], off
	global_load_dwordx4 v[104:107], v[72:73], off offset:192
	v_or_b32_e32 v152, 48, v70
	v_ashrrev_i32_e32 v153, 31, v152
	v_lshl_add_u64 v[152:153], v[152:153], 1, v[68:69]
	global_load_dwordx2 v[188:189], v[152:153], off
	global_load_dwordx4 v[108:111], v[72:73], off offset:224
	v_or_b32_e32 v152, 56, v70
	v_ashrrev_i32_e32 v153, 31, v152
	v_lshl_add_u64 v[152:153], v[152:153], 1, v[68:69]
	global_load_dwordx2 v[190:191], v[152:153], off
	global_load_dwordx4 v[112:115], v[72:73], off offset:256
	v_or_b32_e32 v152, 64, v70
	v_ashrrev_i32_e32 v153, 31, v152
	v_lshl_add_u64 v[152:153], v[152:153], 1, v[68:69]
	global_load_dwordx2 v[192:193], v[152:153], off
	global_load_dwordx4 v[116:119], v[72:73], off offset:288
	v_or_b32_e32 v152, 0x48, v70
	v_ashrrev_i32_e32 v153, 31, v152
	v_lshl_add_u64 v[152:153], v[152:153], 1, v[68:69]
	global_load_dwordx2 v[194:195], v[152:153], off
	global_load_dwordx4 v[120:123], v[72:73], off offset:320
	v_or_b32_e32 v152, 0x50, v70
	v_ashrrev_i32_e32 v153, 31, v152
	v_lshl_add_u64 v[152:153], v[152:153], 1, v[68:69]
	global_load_dwordx2 v[196:197], v[152:153], off
	global_load_dwordx4 v[124:127], v[72:73], off offset:352
	v_or_b32_e32 v152, 0x58, v70
	v_ashrrev_i32_e32 v153, 31, v152
	v_lshl_add_u64 v[152:153], v[152:153], 1, v[68:69]
	global_load_dwordx2 v[198:199], v[152:153], off
	global_load_dwordx4 v[128:131], v[72:73], off offset:384
	v_or_b32_e32 v152, 0x60, v70
	v_ashrrev_i32_e32 v153, 31, v152
	v_lshl_add_u64 v[152:153], v[152:153], 1, v[68:69]
	global_load_dwordx2 v[200:201], v[152:153], off
	global_load_dwordx4 v[132:135], v[72:73], off offset:416
	v_or_b32_e32 v152, 0x68, v70
	v_ashrrev_i32_e32 v153, 31, v152
	v_lshl_add_u64 v[152:153], v[152:153], 1, v[68:69]
	global_load_dwordx2 v[202:203], v[152:153], off
	global_load_dwordx4 v[160:163], v[72:73], off offset:448
	v_or_b32_e32 v152, 0x70, v70
	v_ashrrev_i32_e32 v153, 31, v152
	v_lshl_add_u64 v[152:153], v[152:153], 1, v[68:69]
	global_load_dwordx2 v[204:205], v[152:153], off
	global_load_dwordx4 v[164:167], v[72:73], off offset:480
	v_or_b32_e32 v152, 0x78, v70
	v_ashrrev_i32_e32 v153, 31, v152
	v_lshl_add_u64 v[152:153], v[152:153], 1, v[68:69]
	global_load_dwordx2 v[206:207], v[152:153], off
	v_pk_mul_f32 v[50:51], v[50:51], v[0:1] op_sel_hi:[1,0]
	v_pk_add_f32 v[52:53], v[52:53], v[66:67] op_sel_hi:[1,0] neg_lo:[0,1] neg_hi:[0,1]
	s_mov_b64 s[0:1], 0x2aac1200
	v_pk_mul_f32 v[52:53], v[52:53], v[0:1] op_sel_hi:[1,0]
	v_pk_add_f32 v[54:55], v[54:55], v[66:67] op_sel_hi:[1,0] neg_lo:[0,1] neg_hi:[0,1]
	v_pk_add_f32 v[56:57], v[56:57], v[66:67] op_sel_hi:[1,0] neg_lo:[0,1] neg_hi:[0,1]
	v_pk_mul_f32 v[54:55], v[54:55], v[0:1] op_sel_hi:[1,0]
	v_pk_mul_f32 v[56:57], v[56:57], v[0:1] op_sel_hi:[1,0]
	v_pk_add_f32 v[58:59], v[58:59], v[66:67] op_sel_hi:[1,0] neg_lo:[0,1] neg_hi:[0,1]
	v_pk_add_f32 v[34:35], v[34:35], v[66:67] op_sel_hi:[1,0] neg_lo:[0,1] neg_hi:[0,1]
	v_pk_mul_f32 v[58:59], v[58:59], v[0:1] op_sel_hi:[1,0]
	v_pk_mul_f32 v[34:35], v[34:35], v[0:1] op_sel_hi:[1,0]
	v_pk_add_f32 v[36:37], v[36:37], v[66:67] op_sel_hi:[1,0] neg_lo:[0,1] neg_hi:[0,1]
	v_pk_add_f32 v[38:39], v[38:39], v[66:67] op_sel_hi:[1,0] neg_lo:[0,1] neg_hi:[0,1]
	v_pk_mul_f32 v[36:37], v[36:37], v[0:1] op_sel_hi:[1,0]
	v_pk_mul_f32 v[38:39], v[38:39], v[0:1] op_sel_hi:[1,0]
	v_pk_add_f32 v[18:19], v[18:19], v[66:67] op_sel_hi:[1,0] neg_lo:[0,1] neg_hi:[0,1]
	v_pk_add_f32 v[20:21], v[20:21], v[66:67] op_sel_hi:[1,0] neg_lo:[0,1] neg_hi:[0,1]
	v_pk_mul_f32 v[18:19], v[18:19], v[0:1] op_sel_hi:[1,0]
	v_pk_mul_f32 v[20:21], v[20:21], v[0:1] op_sel_hi:[1,0]
	v_pk_add_f32 v[22:23], v[22:23], v[66:67] op_sel_hi:[1,0] neg_lo:[0,1] neg_hi:[0,1]
	v_pk_add_f32 v[2:3], v[2:3], v[66:67] op_sel_hi:[1,0] neg_lo:[0,1] neg_hi:[0,1]
	v_pk_mul_f32 v[22:23], v[22:23], v[0:1] op_sel_hi:[1,0]
	v_pk_mul_f32 v[2:3], v[2:3], v[0:1] op_sel_hi:[1,0]
	v_pk_add_f32 v[4:5], v[4:5], v[66:67] op_sel_hi:[1,0] neg_lo:[0,1] neg_hi:[0,1]
	v_pk_add_f32 v[6:7], v[6:7], v[66:67] op_sel_hi:[1,0] neg_lo:[0,1] neg_hi:[0,1]
	v_pk_mul_f32 v[4:5], v[4:5], v[0:1] op_sel_hi:[1,0]
	v_pk_mul_f32 v[6:7], v[6:7], v[0:1] op_sel_hi:[1,0]
	s_waitcnt vmcnt(31)
	v_pk_mul_f32 v[50:51], v[74:75], v[50:51]
	v_pk_mul_f32 v[52:53], v[76:77], v[52:53]
	s_waitcnt vmcnt(30)
	v_lshlrev_b32_e32 v74, 16, v82
	v_and_b32_e32 v75, 0xffff0000, v82
	v_pk_mul_f32 v[50:51], v[50:51], v[74:75]
	v_lshlrev_b32_e32 v74, 16, v83
	v_and_b32_e32 v75, 0xffff0000, v83
	v_pk_mul_f32 v[52:53], v[52:53], v[74:75]
	v_cvt_pk_bf16_f32 v74, v50, v51
	v_cvt_pk_bf16_f32 v75, v52, v53
	v_lshl_add_u64 v[52:53], v[78:79], 0, v[80:81]
	v_lshl_add_u64 v[50:51], v[52:53], 0, s[0:1]
	s_mov_b32 s0, 0x2aac1000
	v_add_co_u32_e32 v52, vcc, s0, v52
	s_mov_b64 s[0:1], 0
	s_nop 0
	v_addc_co_u32_e32 v53, vcc, 0, v53, vcc
	global_store_dwordx2 v[52:53], v[74:75], off offset:512
	v_or_b32_e32 v52, 8, v70
	v_ashrrev_i32_e32 v53, 31, v52
	v_lshl_add_u64 v[52:53], v[52:53], 1, v[68:69]
	s_waitcnt vmcnt(30)
	v_pk_mul_f32 v[54:55], v[84:85], v[54:55]
	v_pk_mul_f32 v[56:57], v[86:87], v[56:57]
	s_waitcnt vmcnt(29)
	v_lshlrev_b32_e32 v74, 16, v178
	v_and_b32_e32 v75, 0xffff0000, v178
	v_lshlrev_b32_e32 v52, 16, v179
	v_and_b32_e32 v53, 0xffff0000, v179
	v_pk_mul_f32 v[52:53], v[56:57], v[52:53]
	v_or_b32_e32 v56, 16, v70
	v_pk_mul_f32 v[54:55], v[54:55], v[74:75]
	v_ashrrev_i32_e32 v57, 31, v56
	v_cvt_pk_bf16_f32 v54, v54, v55
	v_cvt_pk_bf16_f32 v55, v52, v53
	v_lshl_add_u64 v[56:57], v[56:57], 1, v[68:69]
	global_store_dwordx2 v[50:51], v[54:55], off offset:16
	s_waitcnt vmcnt(29)
	v_pk_mul_f32 v[52:53], v[88:89], v[58:59]
	s_waitcnt vmcnt(28)
	v_lshlrev_b32_e32 v58, 16, v180
	v_and_b32_e32 v59, 0xffff0000, v180
	v_pk_mul_f32 v[52:53], v[52:53], v[58:59]
	v_pk_add_f32 v[58:59], v[60:61], v[66:67] op_sel_hi:[1,0] neg_lo:[0,1] neg_hi:[0,1]
	v_lshlrev_b32_e32 v56, 16, v181
	v_pk_mul_f32 v[58:59], v[58:59], v[0:1] op_sel_hi:[1,0]
	v_and_b32_e32 v57, 0xffff0000, v181
	v_pk_mul_f32 v[54:55], v[90:91], v[58:59]
	v_cvt_pk_bf16_f32 v52, v52, v53
	v_pk_mul_f32 v[54:55], v[54:55], v[56:57]
	v_or_b32_e32 v56, 24, v70
	v_ashrrev_i32_e32 v57, 31, v56
	v_cvt_pk_bf16_f32 v53, v54, v55
	v_lshl_add_u64 v[56:57], v[56:57], 1, v[68:69]
	global_store_dwordx2 v[50:51], v[52:53], off offset:32
	v_pk_add_f32 v[58:59], v[62:63], v[66:67] op_sel_hi:[1,0] neg_lo:[0,1] neg_hi:[0,1]
	v_pk_mul_f32 v[58:59], v[58:59], v[0:1] op_sel_hi:[1,0]
	s_waitcnt vmcnt(28)
	v_pk_mul_f32 v[52:53], v[92:93], v[58:59]
	s_waitcnt vmcnt(27)
	v_lshlrev_b32_e32 v58, 16, v182
	v_and_b32_e32 v59, 0xffff0000, v182
	v_pk_mul_f32 v[52:53], v[52:53], v[58:59]
	v_pk_add_f32 v[58:59], v[64:65], v[66:67] op_sel_hi:[1,0] neg_lo:[0,1] neg_hi:[0,1]
	v_lshlrev_b32_e32 v56, 16, v183
	v_pk_mul_f32 v[58:59], v[58:59], v[0:1] op_sel_hi:[1,0]
	v_and_b32_e32 v57, 0xffff0000, v183
	v_pk_mul_f32 v[54:55], v[94:95], v[58:59]
	v_cvt_pk_bf16_f32 v52, v52, v53
	v_pk_mul_f32 v[54:55], v[54:55], v[56:57]
	v_or_b32_e32 v56, 32, v70
	v_ashrrev_i32_e32 v57, 31, v56
	v_cvt_pk_bf16_f32 v53, v54, v55
	v_lshl_add_u64 v[56:57], v[56:57], 1, v[68:69]
	global_store_dwordx2 v[50:51], v[52:53], off offset:48
	s_waitcnt vmcnt(27)
	v_pk_mul_f32 v[34:35], v[34:35], v[96:97]
	v_pk_mul_f32 v[36:37], v[36:37], v[98:99]
	s_waitcnt vmcnt(26)
	v_lshlrev_b32_e32 v52, 16, v184
	v_and_b32_e32 v53, 0xffff0000, v184
	v_pk_mul_f32 v[34:35], v[34:35], v[52:53]
	v_lshlrev_b32_e32 v52, 16, v185
	v_and_b32_e32 v53, 0xffff0000, v185
	v_pk_mul_f32 v[36:37], v[36:37], v[52:53]
	v_or_b32_e32 v52, 40, v70
	v_ashrrev_i32_e32 v53, 31, v52
	v_cvt_pk_bf16_f32 v34, v34, v35
	v_cvt_pk_bf16_f32 v35, v36, v37
	v_lshl_add_u64 v[52:53], v[52:53], 1, v[68:69]
	global_store_dwordx2 v[50:51], v[34:35], off offset:64
	s_waitcnt vmcnt(26)
	v_pk_mul_f32 v[34:35], v[38:39], v[100:101]
	s_waitcnt vmcnt(25)
	v_lshlrev_b32_e32 v38, 16, v186
	v_and_b32_e32 v39, 0xffff0000, v186
	v_pk_mul_f32 v[34:35], v[34:35], v[38:39]
	v_pk_add_f32 v[38:39], v[40:41], v[66:67] op_sel_hi:[1,0] neg_lo:[0,1] neg_hi:[0,1]
	v_cvt_pk_bf16_f32 v34, v34, v35
	v_pk_mul_f32 v[38:39], v[38:39], v[0:1] op_sel_hi:[1,0]
	v_pk_add_f32 v[40:41], v[42:43], v[66:67] op_sel_hi:[1,0] neg_lo:[0,1] neg_hi:[0,1]
	v_pk_mul_f32 v[36:37], v[38:39], v[102:103]
	v_lshlrev_b32_e32 v38, 16, v187
	v_and_b32_e32 v39, 0xffff0000, v187
	v_pk_mul_f32 v[36:37], v[36:37], v[38:39]
	v_or_b32_e32 v38, 48, v70
	v_ashrrev_i32_e32 v39, 31, v38
	v_cvt_pk_bf16_f32 v35, v36, v37
	v_lshl_add_u64 v[38:39], v[38:39], 1, v[68:69]
	global_store_dwordx2 v[50:51], v[34:35], off offset:80
	v_pk_mul_f32 v[40:41], v[40:41], v[0:1] op_sel_hi:[1,0]
	s_waitcnt vmcnt(25)
	v_pk_mul_f32 v[34:35], v[40:41], v[104:105]
	s_waitcnt vmcnt(24)
	v_lshlrev_b32_e32 v40, 16, v188
	v_and_b32_e32 v41, 0xffff0000, v188
	v_pk_mul_f32 v[34:35], v[34:35], v[40:41]
	v_pk_add_f32 v[40:41], v[44:45], v[66:67] op_sel_hi:[1,0] neg_lo:[0,1] neg_hi:[0,1]
	v_lshlrev_b32_e32 v38, 16, v189
	v_pk_mul_f32 v[40:41], v[40:41], v[0:1] op_sel_hi:[1,0]
	v_and_b32_e32 v39, 0xffff0000, v189
	v_pk_mul_f32 v[36:37], v[40:41], v[106:107]
	v_cvt_pk_bf16_f32 v34, v34, v35
	v_pk_mul_f32 v[36:37], v[36:37], v[38:39]
	v_or_b32_e32 v38, 56, v70
	v_ashrrev_i32_e32 v39, 31, v38
	v_cvt_pk_bf16_f32 v35, v36, v37
	v_lshl_add_u64 v[38:39], v[38:39], 1, v[68:69]
	global_store_dwordx2 v[50:51], v[34:35], off offset:96
	v_pk_add_f32 v[40:41], v[46:47], v[66:67] op_sel_hi:[1,0] neg_lo:[0,1] neg_hi:[0,1]
	v_pk_mul_f32 v[40:41], v[40:41], v[0:1] op_sel_hi:[1,0]
	s_waitcnt vmcnt(24)
	v_pk_mul_f32 v[34:35], v[40:41], v[108:109]
	s_waitcnt vmcnt(23)
	v_lshlrev_b32_e32 v40, 16, v190
	v_and_b32_e32 v41, 0xffff0000, v190
	v_pk_mul_f32 v[34:35], v[34:35], v[40:41]
	v_pk_add_f32 v[40:41], v[48:49], v[66:67] op_sel_hi:[1,0] neg_lo:[0,1] neg_hi:[0,1]
	v_lshlrev_b32_e32 v38, 16, v191
	v_pk_mul_f32 v[40:41], v[40:41], v[0:1] op_sel_hi:[1,0]
	v_and_b32_e32 v39, 0xffff0000, v191
	v_pk_mul_f32 v[36:37], v[40:41], v[110:111]
	v_cvt_pk_bf16_f32 v34, v34, v35
	v_pk_mul_f32 v[36:37], v[36:37], v[38:39]
	v_or_b32_e32 v38, 64, v70
	v_ashrrev_i32_e32 v39, 31, v38
	v_cvt_pk_bf16_f32 v35, v36, v37
	v_lshl_add_u64 v[38:39], v[38:39], 1, v[68:69]
	global_store_dwordx2 v[50:51], v[34:35], off offset:112
	s_waitcnt vmcnt(23)
	v_pk_mul_f32 v[18:19], v[18:19], v[112:113]
	v_pk_mul_f32 v[20:21], v[20:21], v[114:115]
	s_waitcnt vmcnt(22)
	v_lshlrev_b32_e32 v34, 16, v192
	v_and_b32_e32 v35, 0xffff0000, v192
	v_pk_mul_f32 v[18:19], v[18:19], v[34:35]
	v_lshlrev_b32_e32 v34, 16, v193
	v_and_b32_e32 v35, 0xffff0000, v193
	v_pk_mul_f32 v[20:21], v[20:21], v[34:35]
	v_or_b32_e32 v34, 0x48, v70
	v_ashrrev_i32_e32 v35, 31, v34
	v_cvt_pk_bf16_f32 v18, v18, v19
	v_cvt_pk_bf16_f32 v19, v20, v21
	v_lshl_add_u64 v[34:35], v[34:35], 1, v[68:69]
	global_store_dwordx2 v[50:51], v[18:19], off offset:128
	s_waitcnt vmcnt(22)
	v_pk_mul_f32 v[18:19], v[22:23], v[116:117]
	s_waitcnt vmcnt(21)
	v_lshlrev_b32_e32 v22, 16, v194
	v_and_b32_e32 v23, 0xffff0000, v194
	v_pk_mul_f32 v[18:19], v[18:19], v[22:23]
	v_pk_add_f32 v[22:23], v[24:25], v[66:67] op_sel_hi:[1,0] neg_lo:[0,1] neg_hi:[0,1]
	v_cvt_pk_bf16_f32 v18, v18, v19
	v_pk_mul_f32 v[22:23], v[22:23], v[0:1] op_sel_hi:[1,0]
	v_pk_add_f32 v[24:25], v[26:27], v[66:67] op_sel_hi:[1,0] neg_lo:[0,1] neg_hi:[0,1]
	v_pk_mul_f32 v[20:21], v[22:23], v[118:119]
	v_lshlrev_b32_e32 v22, 16, v195
	v_and_b32_e32 v23, 0xffff0000, v195
	v_pk_mul_f32 v[20:21], v[20:21], v[22:23]
	v_or_b32_e32 v22, 0x50, v70
	v_ashrrev_i32_e32 v23, 31, v22
	v_cvt_pk_bf16_f32 v19, v20, v21
	v_lshl_add_u64 v[22:23], v[22:23], 1, v[68:69]
	global_store_dwordx2 v[50:51], v[18:19], off offset:144
	v_pk_mul_f32 v[24:25], v[24:25], v[0:1] op_sel_hi:[1,0]
	s_waitcnt vmcnt(21)
	v_pk_mul_f32 v[18:19], v[24:25], v[120:121]
	s_waitcnt vmcnt(20)
	v_lshlrev_b32_e32 v24, 16, v196
	v_and_b32_e32 v25, 0xffff0000, v196
	v_pk_mul_f32 v[18:19], v[18:19], v[24:25]
	v_pk_add_f32 v[24:25], v[28:29], v[66:67] op_sel_hi:[1,0] neg_lo:[0,1] neg_hi:[0,1]
	v_lshlrev_b32_e32 v22, 16, v197
	v_pk_mul_f32 v[24:25], v[24:25], v[0:1] op_sel_hi:[1,0]
	v_and_b32_e32 v23, 0xffff0000, v197
	v_pk_mul_f32 v[20:21], v[24:25], v[122:123]
	v_cvt_pk_bf16_f32 v18, v18, v19
	v_pk_mul_f32 v[20:21], v[20:21], v[22:23]
	v_or_b32_e32 v22, 0x58, v70
	v_ashrrev_i32_e32 v23, 31, v22
	v_cvt_pk_bf16_f32 v19, v20, v21
	v_lshl_add_u64 v[22:23], v[22:23], 1, v[68:69]
	global_store_dwordx2 v[50:51], v[18:19], off offset:160
	v_pk_add_f32 v[24:25], v[30:31], v[66:67] op_sel_hi:[1,0] neg_lo:[0,1] neg_hi:[0,1]
	v_pk_mul_f32 v[24:25], v[24:25], v[0:1] op_sel_hi:[1,0]
	s_waitcnt vmcnt(20)
	v_pk_mul_f32 v[18:19], v[24:25], v[124:125]
	s_waitcnt vmcnt(19)
	v_lshlrev_b32_e32 v24, 16, v198
	v_and_b32_e32 v25, 0xffff0000, v198
	v_pk_mul_f32 v[18:19], v[18:19], v[24:25]
	v_pk_add_f32 v[24:25], v[32:33], v[66:67] op_sel_hi:[1,0] neg_lo:[0,1] neg_hi:[0,1]
	v_lshlrev_b32_e32 v22, 16, v199
	v_pk_mul_f32 v[24:25], v[24:25], v[0:1] op_sel_hi:[1,0]
	v_and_b32_e32 v23, 0xffff0000, v199
	v_pk_mul_f32 v[20:21], v[24:25], v[126:127]
	v_cvt_pk_bf16_f32 v18, v18, v19
	v_pk_mul_f32 v[20:21], v[20:21], v[22:23]
	v_or_b32_e32 v22, 0x60, v70
	v_ashrrev_i32_e32 v23, 31, v22
	v_cvt_pk_bf16_f32 v19, v20, v21
	v_lshl_add_u64 v[22:23], v[22:23], 1, v[68:69]
	global_store_dwordx2 v[50:51], v[18:19], off offset:176
	s_waitcnt vmcnt(19)
	v_pk_mul_f32 v[2:3], v[2:3], v[128:129]
	v_pk_mul_f32 v[4:5], v[4:5], v[130:131]
	s_waitcnt vmcnt(18)
	v_lshlrev_b32_e32 v18, 16, v200
	v_and_b32_e32 v19, 0xffff0000, v200
	v_pk_mul_f32 v[2:3], v[2:3], v[18:19]
	v_lshlrev_b32_e32 v18, 16, v201
	v_and_b32_e32 v19, 0xffff0000, v201
	v_pk_mul_f32 v[4:5], v[4:5], v[18:19]
	v_or_b32_e32 v18, 0x68, v70
	v_ashrrev_i32_e32 v19, 31, v18
	v_cvt_pk_bf16_f32 v2, v2, v3
	v_cvt_pk_bf16_f32 v3, v4, v5
	v_lshl_add_u64 v[18:19], v[18:19], 1, v[68:69]
	global_store_dwordx2 v[50:51], v[2:3], off offset:192
	s_waitcnt vmcnt(18)
	v_pk_mul_f32 v[2:3], v[6:7], v[132:133]
	s_waitcnt vmcnt(17)
	v_lshlrev_b32_e32 v6, 16, v202
	v_and_b32_e32 v7, 0xffff0000, v202
	v_pk_mul_f32 v[2:3], v[2:3], v[6:7]
	v_pk_add_f32 v[6:7], v[8:9], v[66:67] op_sel_hi:[1,0] neg_lo:[0,1] neg_hi:[0,1]
	v_cvt_pk_bf16_f32 v2, v2, v3
	v_pk_mul_f32 v[6:7], v[6:7], v[0:1] op_sel_hi:[1,0]
	v_pk_add_f32 v[8:9], v[10:11], v[66:67] op_sel_hi:[1,0] neg_lo:[0,1] neg_hi:[0,1]
	v_pk_mul_f32 v[4:5], v[6:7], v[134:135]
	v_lshlrev_b32_e32 v6, 16, v203
	v_and_b32_e32 v7, 0xffff0000, v203
	v_pk_mul_f32 v[4:5], v[4:5], v[6:7]
	v_or_b32_e32 v6, 0x70, v70
	v_ashrrev_i32_e32 v7, 31, v6
	v_cvt_pk_bf16_f32 v3, v4, v5
	v_lshl_add_u64 v[6:7], v[6:7], 1, v[68:69]
	global_store_dwordx2 v[50:51], v[2:3], off offset:208
	v_pk_mul_f32 v[8:9], v[8:9], v[0:1] op_sel_hi:[1,0]
	s_waitcnt vmcnt(17)
	v_pk_mul_f32 v[2:3], v[8:9], v[160:161]
	s_waitcnt vmcnt(16)
	v_lshlrev_b32_e32 v8, 16, v204
	v_and_b32_e32 v9, 0xffff0000, v204
	v_pk_mul_f32 v[2:3], v[2:3], v[8:9]
	v_pk_add_f32 v[8:9], v[12:13], v[66:67] op_sel_hi:[1,0] neg_lo:[0,1] neg_hi:[0,1]
	v_lshlrev_b32_e32 v6, 16, v205
	v_pk_mul_f32 v[8:9], v[8:9], v[0:1] op_sel_hi:[1,0]
	v_and_b32_e32 v7, 0xffff0000, v205
	v_pk_mul_f32 v[4:5], v[8:9], v[162:163]
	v_cvt_pk_bf16_f32 v2, v2, v3
	v_pk_mul_f32 v[4:5], v[4:5], v[6:7]
	v_or_b32_e32 v6, 0x78, v70
	v_ashrrev_i32_e32 v7, 31, v6
	v_cvt_pk_bf16_f32 v3, v4, v5
	v_lshl_add_u64 v[6:7], v[6:7], 1, v[68:69]
	global_store_dwordx2 v[50:51], v[2:3], off offset:224
	v_pk_add_f32 v[8:9], v[14:15], v[66:67] op_sel_hi:[1,0] neg_lo:[0,1] neg_hi:[0,1]
	v_pk_mul_f32 v[8:9], v[8:9], v[0:1] op_sel_hi:[1,0]
	s_waitcnt vmcnt(16)
	v_pk_mul_f32 v[2:3], v[8:9], v[164:165]
	s_waitcnt vmcnt(15)
	v_lshlrev_b32_e32 v8, 16, v206
	v_and_b32_e32 v9, 0xffff0000, v206
	v_pk_mul_f32 v[2:3], v[2:3], v[8:9]
	v_pk_add_f32 v[8:9], v[16:17], v[66:67] op_sel_hi:[1,0] neg_lo:[0,1] neg_hi:[0,1]
	v_lshlrev_b32_e32 v6, 16, v207
	v_pk_mul_f32 v[8:9], v[8:9], v[0:1] op_sel_hi:[1,0]
	v_and_b32_e32 v7, 0xffff0000, v207
	v_pk_mul_f32 v[4:5], v[8:9], v[166:167]
	v_cvt_pk_bf16_f32 v2, v2, v3
	v_pk_mul_f32 v[4:5], v[4:5], v[6:7]
	s_nop 0
	v_cvt_pk_bf16_f32 v3, v4, v5
	global_store_dwordx2 v[50:51], v[2:3], off offset:240
	v_mov_b32_e32 v76, v86
	v_mov_b32_e32 v77, v87
	v_mov_b32_e32 v54, v98
	v_mov_b32_e32 v55, v99
	v_mov_b32_e32 v56, v184
	v_mov_b32_e32 v57, v185
	v_mov_b32_e32 v52, v186
	v_mov_b32_e32 v53, v187
	v_mov_b32_e32 v36, v114
	v_mov_b32_e32 v37, v115
	v_mov_b32_e32 v38, v192
	v_mov_b32_e32 v39, v193
	v_mov_b32_e32 v34, v194
	v_mov_b32_e32 v35, v195
	v_mov_b32_e32 v20, v130
	v_mov_b32_e32 v21, v131
	v_mov_b32_e32 v22, v200
	v_mov_b32_e32 v23, v201
	v_mov_b32_e32 v18, v202
	v_mov_b32_e32 v19, v203
	s_barrier
